# accumulator zeroing with v_mov_b64 pairs (3 GEMM unit headers), on v19
# speedup vs baseline: 1.0172x; 1.0011x over previous
.LBB0_576:
	s_ashr_i32 s25, s24, 31
	s_lshl_b64 s[0:1], s[24:25], 19
	s_add_u32 s28, s96, s0
	s_addc_u32 s29, s97, s1
	s_and_b64 s[0:1], s[36:37], exec
	s_cselect_b32 s25, s29, s47
	s_cselect_b32 s43, s28, s46
	s_ashr_i32 s27, s26, 31
	s_lshl_b64 s[0:1], s[26:27], 19
	v_readlane_b32 s30, v255, 7
	v_readlane_b32 s31, v255, 8
	s_add_u32 s30, s30, s0
	s_addc_u32 s31, s31, s1
	s_and_b64 s[0:1], s[36:37], exec
	s_cselect_b32 s27, s31, s45
	s_cselect_b32 s53, s30, s44
	s_add_u32 s72, s44, 0x100
	s_addc_u32 s73, s45, 0
	s_add_u32 s0, s46, 0x40080
	v_mov_b32_e32 v2, 0
	s_addc_u32 s1, s47, 0
	s_mov_b32 s74, -2
	v_mov_b32_e32 v3, v2
	v_mov_b64_e32 v[4:5], 0
	v_mov_b64_e32 v[6:7], 0
	v_mov_b64_e32 v[8:9], 0
	v_mov_b64_e32 v[10:11], 0
	v_mov_b64_e32 v[12:13], 0
	v_mov_b64_e32 v[14:15], 0
	v_mov_b64_e32 v[16:17], 0
	v_mov_b64_e32 v[18:19], 0
	v_mov_b64_e32 v[20:21], 0
	v_mov_b64_e32 v[22:23], 0
	v_mov_b64_e32 v[24:25], 0
	v_mov_b64_e32 v[26:27], 0
	v_mov_b64_e32 v[28:29], 0
	v_mov_b64_e32 v[30:31], 0
	v_mov_b64_e32 v[32:33], 0
	v_mov_b64_e32 v[34:35], 0
	v_mov_b64_e32 v[36:37], 0
	v_mov_b64_e32 v[38:39], 0
	v_mov_b64_e32 v[40:41], 0
	v_mov_b64_e32 v[42:43], 0
	v_mov_b64_e32 v[44:45], 0
	v_mov_b64_e32 v[46:47], 0
	v_mov_b64_e32 v[48:49], 0
	v_mov_b64_e32 v[50:51], 0
	v_mov_b64_e32 v[52:53], 0
	v_mov_b64_e32 v[54:55], 0
	v_mov_b64_e32 v[56:57], 0
	v_mov_b64_e32 v[58:59], 0
	v_mov_b64_e32 v[60:61], 0
	v_mov_b64_e32 v[62:63], 0
	v_mov_b64_e32 v[64:65], 0
	v_mov_b64_e32 v[66:67], 0
	v_mov_b64_e32 v[68:69], 0
	v_mov_b64_e32 v[78:79], 0
	v_mov_b64_e32 v[80:81], 0
	v_mov_b64_e32 v[98:99], 0
	v_mov_b64_e32 v[100:101], 0
	v_mov_b64_e32 v[110:111], 0
	v_mov_b64_e32 v[112:113], 0
	v_mov_b64_e32 v[114:115], 0
	v_mov_b64_e32 v[116:117], 0
	v_mov_b64_e32 v[118:119], 0
	v_mov_b64_e32 v[120:121], 0
	v_mov_b64_e32 v[122:123], 0
	v_mov_b64_e32 v[124:125], 0
	v_mov_b64_e32 v[126:127], 0
	v_mov_b64_e32 v[128:129], 0
	v_mov_b64_e32 v[130:131], 0
	v_mov_b64_e32 v[132:133], 0
	v_mov_b64_e32 v[134:135], 0
	v_mov_b64_e32 v[136:137], 0
	v_mov_b64_e32 v[138:139], 0
	v_mov_b64_e32 v[140:141], 0
	v_mov_b64_e32 v[142:143], 0
	v_mov_b64_e32 v[144:145], 0
	v_mov_b64_e32 v[146:147], 0
	v_mov_b64_e32 v[148:149], 0
	v_mov_b64_e32 v[150:151], 0
	v_mov_b64_e32 v[152:153], 0
	v_mov_b64_e32 v[154:155], 0
	v_mov_b64_e32 v[156:157], 0
	v_mov_b64_e32 v[158:159], 0
	v_mov_b64_e32 v[160:161], 0

.LBB0_803:
	s_add_u32 s3, s30, 0x100
	s_addc_u32 s43, s31, 0
	s_add_u32 s30, s40, 0x80
	v_mov_b32_e32 v2, 0
	s_addc_u32 s31, s41, 0
	s_mov_b32 s36, 0
	v_mov_b32_e32 v3, v2
	s_waitcnt lgkmcnt(0)
	v_mov_b64_e32 v[4:5], 0
	v_mov_b64_e32 v[6:7], 0
	v_mov_b64_e32 v[8:9], 0
	v_mov_b64_e32 v[10:11], 0
	v_mov_b64_e32 v[12:13], 0
	v_mov_b64_e32 v[14:15], 0
	v_mov_b64_e32 v[16:17], 0
	v_mov_b64_e32 v[18:19], 0
	v_mov_b64_e32 v[20:21], 0
	v_mov_b64_e32 v[22:23], 0
	v_mov_b64_e32 v[24:25], 0
	v_mov_b64_e32 v[26:27], 0
	v_mov_b64_e32 v[28:29], 0
	v_mov_b64_e32 v[30:31], 0
	v_mov_b64_e32 v[32:33], 0
	v_mov_b64_e32 v[34:35], 0
	v_mov_b64_e32 v[36:37], 0
	v_mov_b64_e32 v[38:39], 0
	v_mov_b64_e32 v[40:41], 0
	v_mov_b64_e32 v[42:43], 0
	v_mov_b64_e32 v[44:45], 0
	v_mov_b64_e32 v[46:47], 0
	v_mov_b64_e32 v[48:49], 0
	v_mov_b64_e32 v[50:51], 0
	v_mov_b64_e32 v[52:53], 0
	v_mov_b64_e32 v[54:55], 0
	v_mov_b64_e32 v[56:57], 0
	v_mov_b64_e32 v[58:59], 0
	v_mov_b64_e32 v[60:61], 0
	v_mov_b64_e32 v[62:63], 0
	v_mov_b64_e32 v[64:65], 0
	v_mov_b64_e32 v[82:83], 0
	v_mov_b64_e32 v[84:85], 0
	v_mov_b64_e32 v[94:95], 0
	v_mov_b64_e32 v[96:97], 0
	v_mov_b64_e32 v[106:107], 0
	v_mov_b64_e32 v[108:109], 0
	v_mov_b64_e32 v[110:111], 0
	v_mov_b64_e32 v[112:113], 0
	v_mov_b64_e32 v[114:115], 0
	v_mov_b64_e32 v[116:117], 0
	v_mov_b64_e32 v[118:119], 0
	v_mov_b64_e32 v[120:121], 0
	v_mov_b64_e32 v[122:123], 0
	v_mov_b64_e32 v[124:125], 0
	v_mov_b64_e32 v[126:127], 0
	v_mov_b64_e32 v[128:129], 0
	v_mov_b64_e32 v[130:131], 0
	v_mov_b64_e32 v[132:133], 0
	v_mov_b64_e32 v[134:135], 0
	v_mov_b64_e32 v[136:137], 0
	v_mov_b64_e32 v[138:139], 0
	v_mov_b64_e32 v[140:141], 0
	v_mov_b64_e32 v[142:143], 0
	v_mov_b64_e32 v[144:145], 0
	v_mov_b64_e32 v[146:147], 0
	v_mov_b64_e32 v[148:149], 0
	v_mov_b64_e32 v[150:151], 0
	v_mov_b64_e32 v[152:153], 0
	v_mov_b64_e32 v[154:155], 0
	v_mov_b64_e32 v[156:157], 0
	v_mov_b64_e32 v[158:159], 0
	v_mov_b64_e32 v[160:161], 0

.LBB0_944:
	s_ashr_i32 s23, s22, 31
	s_lshl_b64 s[26:27], s[22:23], 19
	s_add_u32 s26, s96, s26
	s_addc_u32 s27, s97, s27
	s_and_b64 s[28:29], s[0:1], exec
	s_cselect_b32 s23, s27, s41
	s_cselect_b32 s56, s26, s40
	s_ashr_i32 s25, s24, 31
	s_lshl_b64 s[28:29], s[24:25], 19
	s_add_u32 s28, s16, s28
	s_addc_u32 s29, s17, s29
	s_and_b64 s[42:43], s[0:1], exec
	s_cselect_b32 s25, s29, s39
	s_cselect_b32 s57, s28, s38
	s_add_u32 s61, s38, 0x100
	s_addc_u32 s63, s39, 0
	s_add_u32 s38, s40, 0x40080
	v_mov_b32_e32 v2, 0
	s_addc_u32 s39, s41, 0
	s_mov_b32 s68, -2
	v_mov_b32_e32 v3, v2
	v_mov_b64_e32 v[4:5], 0
	v_mov_b64_e32 v[6:7], 0
	v_mov_b64_e32 v[8:9], 0
	v_mov_b64_e32 v[10:11], 0
	v_mov_b64_e32 v[12:13], 0
	v_mov_b64_e32 v[14:15], 0
	v_mov_b64_e32 v[16:17], 0
	v_mov_b64_e32 v[18:19], 0
	v_mov_b64_e32 v[20:21], 0
	v_mov_b64_e32 v[22:23], 0
	v_mov_b64_e32 v[24:25], 0
	v_mov_b64_e32 v[26:27], 0
	v_mov_b64_e32 v[28:29], 0
	v_mov_b64_e32 v[30:31], 0
	v_mov_b64_e32 v[32:33], 0
	v_mov_b64_e32 v[34:35], 0
	v_mov_b64_e32 v[36:37], 0
	v_mov_b64_e32 v[38:39], 0
	v_mov_b64_e32 v[40:41], 0
	v_mov_b64_e32 v[42:43], 0
	v_mov_b64_e32 v[44:45], 0
	v_mov_b64_e32 v[46:47], 0
	v_mov_b64_e32 v[48:49], 0
	v_mov_b64_e32 v[50:51], 0
	v_mov_b64_e32 v[52:53], 0
	v_mov_b64_e32 v[54:55], 0
	v_mov_b64_e32 v[56:57], 0
	v_mov_b64_e32 v[58:59], 0
	v_mov_b64_e32 v[60:61], 0
	v_mov_b64_e32 v[62:63], 0
	v_mov_b64_e32 v[64:65], 0
	v_mov_b64_e32 v[66:67], 0
	v_mov_b64_e32 v[68:69], 0
	v_mov_b64_e32 v[70:71], 0
	v_mov_b64_e32 v[72:73], 0
	v_mov_b64_e32 v[74:75], 0
	v_mov_b64_e32 v[76:77], 0
	v_mov_b64_e32 v[78:79], 0
	v_mov_b64_e32 v[80:81], 0
	v_mov_b64_e32 v[82:83], 0
	v_mov_b64_e32 v[84:85], 0
	v_mov_b64_e32 v[86:87], 0
	v_mov_b64_e32 v[88:89], 0
	v_mov_b64_e32 v[90:91], 0
	v_mov_b64_e32 v[92:93], 0
	v_mov_b64_e32 v[94:95], 0
	v_mov_b64_e32 v[96:97], 0
	v_mov_b64_e32 v[98:99], 0
	v_mov_b64_e32 v[100:101], 0
	v_mov_b64_e32 v[102:103], 0
	v_mov_b64_e32 v[104:105], 0
	v_mov_b64_e32 v[106:107], 0
	v_mov_b64_e32 v[108:109], 0
	v_mov_b64_e32 v[118:119], 0
	v_mov_b64_e32 v[120:121], 0
	v_mov_b64_e32 v[130:131], 0
	v_mov_b64_e32 v[132:133], 0
	v_mov_b64_e32 v[150:151], 0
	v_mov_b64_e32 v[152:153], 0
	v_mov_b64_e32 v[154:155], 0
	v_mov_b64_e32 v[156:157], 0
	v_mov_b64_e32 v[158:159], 0
	v_mov_b64_e32 v[160:161], 0
